# v38: v33 + static priority raise for waves 4-7 during P2 (q/k norm + rope + pooling)
# speedup vs baseline: 1.0036x; 1.0036x over previous
; __device__ __forceinline__ CArgs* phase_args() { CArgs* p = (CArgs*)__builtin_amdgcn_kernarg_segment_ptr(); asm volatile("" : "+s"(p)); return p; }
; #define P2_LOAD(dst, row_) do { const bf16_t* pr_ = PROJ + (size_t)(row_) * INW + 1024 + hq * 128 + sub * 4; _Pragma("unroll") for (int p_ = 0; p_ < 4; ++p_) { dst[2 * p_] = *(const u32x2*)(pr_ + p_ * 512); dst[2 * p_ + 1] = *(const u32x2*)(pr_ + p_ * 512 + 64); } } while (0)
; __global__ void __launch_bounds__(512, 2) mega_fwd(Args args) {
;     ...
;     if (IN(2)) { CArgs* pa = phase_args();
;         {
;             const int sub = lane & 15, hq = lane >> 4;
;     ...
;             u32x2 ra[8], rn[8];
;             int row = gw;
;             if (row < MR) P2_LOAD(ra, row);
;             for (; row < MR; row += NGW) {
;                 const int nrow = row + NGW;
; #pragma unroll
;                 for (int i = 0; i < 8; ++i) rn[i] = ra[i];
;                 if (nrow < MR) P2_LOAD(rn, nrow);
;     ...
;                 for (int e = 0; e < 4; ++e) { const double t = (double)pos * INVF[sub * 4 + e] * 0.15915494309189535; const float fr = (float)(t - rint(t));
;                     cs[e] = __builtin_amdgcn_cosf(fr); sn[e] = __builtin_amdgcn_sinf(fr); }
.LBB0_164:
.LBB0_165:
	s_cmp_lt_i32 s24, 3
	s_cselect_b64 s[4:5], -1, 0
	s_cmp_gt_i32 s25, 2
	s_cselect_b64 s[6:7], -1, 0
	s_and_b64 s[4:5], s[4:5], s[6:7]
	s_andn2_b64 vcc, exec, s[4:5]
	v_and_b32_e32 v196, 15, v193
	s_cbranch_vccnz .LBB0_336
	s_mov_b64 s[8:9], s[0:1]
	s_cmp_ge_u32 s80, 4
	s_cbranch_scc0 .Lp2_prio_done
	s_setprio 1
.Lp2_prio_done:
	s_cmpk_gt_i32 s12, 0x407f
	v_lshlrev_b32_e32 v92, 5, v196
	s_cbranch_scc1 .LBB0_175
	s_load_dwordx2 s[20:21], s[8:9], 0xf8
	s_load_dwordx4 s[4:7], s[8:9], 0x58
	s_ashr_i32 s13, s12, 31
	s_lshl_b64 s[10:11], s[12:13], 13
	v_lshrrev_b32_e32 v20, 4, v192
	s_waitcnt lgkmcnt(0)
	s_add_u32 s18, s20, s10
	s_addc_u32 s19, s21, s11
	v_mov_b32_e32 v17, 0
	v_lshlrev_b32_e32 v16, 8, v20
	v_lshl_add_u64 v[0:1], s[18:19], 0, v[16:17]
	v_lshlrev_b32_e32 v18, 3, v196
	v_mov_b32_e32 v19, v17
	v_lshl_add_u64 v[0:1], v[0:1], 0, v[18:19]
	s_mov_b64 s[10:11], 0x15d00800
	v_lshl_add_u64 v[2:3], v[0:1], 0, s[10:11]
	s_mov_b32 s10, 0x15d00000
	v_add_co_u32_e32 v0, vcc, s10, v0
	s_getpc_b64 s[10:11]
	s_add_u32 s10, s10, _ZL4INVF@rel32@lo+4
	s_addc_u32 s11, s11, _ZL4INVF@rel32@hi+12
	v_addc_co_u32_e32 v1, vcc, 0, v1, vcc
	global_load_dwordx2 v[60:61], v[0:1], off offset:2048
	global_load_dwordx2 v[58:59], v[2:3], off offset:128
	global_load_dwordx2 v[14:15], v[2:3], off offset:1024
	global_load_dwordx2 v[12:13], v[2:3], off offset:1152
	global_load_dwordx2 v[10:11], v[2:3], off offset:2048
	global_load_dwordx2 v[8:9], v[2:3], off offset:2176
	global_load_dwordx2 v[56:57], v[2:3], off offset:3072
	global_load_dwordx2 v[54:55], v[2:3], off offset:3200
	s_nop 0
	global_load_dwordx4 v[0:3], v92, s[10:11] offset:16
	global_load_dwordx4 v[4:7], v92, s[10:11]
	v_mbcnt_lo_u32_b32 v16, -1, 0
	v_mbcnt_hi_u32_b32 v16, -1, v16
	v_and_b32_e32 v22, 64, v16
	v_xor_b32_e32 v21, 1, v16
	v_add_u32_e32 v22, 64, v22
	v_cmp_lt_i32_e32 vcc, v21, v22
	v_xor_b32_e32 v23, 2, v16
	s_bfe_u32 s23, s39, 0x20006
	v_cndmask_b32_e32 v21, v16, v21, vcc
	v_cmp_lt_i32_e32 vcc, v23, v22
	s_ashr_i32 s15, s14, 31
	s_bitset1_b32 s23, 14
	v_cndmask_b32_e32 v23, v16, v23, vcc
	v_lshlrev_b32_e32 v35, 2, v23
	v_xor_b32_e32 v23, 4, v16
	v_cmp_lt_i32_e32 vcc, v23, v22
	s_movk_i32 s10, 0x700
	v_mov_b32_e32 v28, 0x400
	v_cndmask_b32_e32 v23, v16, v23, vcc
	v_lshlrev_b32_e32 v68, 2, v23
	v_xor_b32_e32 v23, 8, v16
	v_cmp_lt_i32_e32 vcc, v23, v22
	v_lshlrev_b32_e32 v36, 7, v20
	v_lshlrev_b32_e32 v38, 3, v192
	v_cndmask_b32_e32 v16, v16, v23, vcc
	v_lshlrev_b32_e32 v69, 2, v16
	v_lshlrev_b32_e32 v16, 4, v196
	v_lshl_add_u64 v[22:23], s[4:5], 0, v[16:17]
	v_lshl_add_u64 v[24:25], s[6:7], 0, v[16:17]
	v_lshlrev_b32_e32 v16, 4, v192
	v_lshl_add_u64 v[26:27], s[18:19], 0, v[16:17]
	s_mov_b64 s[4:5], 0x15d01c00
	v_lshl_add_u64 v[26:27], v[26:27], 0, s[4:5]
	s_lshl_b64 s[6:7], s[14:15], 13
	s_lshl_b64 s[4:5], s[12:13], 11
	s_lshl_b64 s[18:19], s[14:15], 11
	s_add_u32 s4, s20, s4
	v_bitop3_b32 v16, v16, s10, v28 bitop3:0xc8
	s_addc_u32 s5, s21, s5
	v_lshl_add_u64 v[28:29], s[4:5], 0, v[16:17]
	v_and_b32_e32 v16, 48, v193
	v_lshlrev_b32_e32 v16, 4, v16
	v_lshl_add_u64 v[30:31], s[4:5], 0, v[16:17]
	s_add_i32 s4, s12, s14
	s_ashr_i32 s5, s4, 31
	v_or_b32_e32 v40, 0x600, v36
	s_lshl_b64 s[4:5], s[4:5], 13
	s_mov_b32 s20, 0x6dc9c883
	v_lshlrev_b32_e32 v20, 2, v196
	s_mov_b32 s11, 0
	v_lshlrev_b32_e32 v21, 2, v21
	v_or_b32_e32 v32, s4, v16
	v_mov_b32_e32 v33, s5
	s_mov_b32 s21, 0x3fc45f30
	v_mov_b32_e32 v34, 0x358637bd
	s_brev_b32 s22, 60
	s_mov_b32 s13, 0x800000
	s_mov_b32 s15, 0x1df00000
	s_mov_b32 s27, 0x810f000
	v_lshlrev_b32_e32 v16, 2, v36
	v_lshlrev_b32_e32 v36, 2, v40
	s_mov_b32 s33, 0x890f000
	v_lshlrev_b32_e32 v70, 2, v38
	s_mov_b32 s4, s12
	s_waitcnt vmcnt(0)
	v_mov_b64_e32 v[38:39], v[60:61]
	v_mov_b64_e32 v[40:41], v[58:59]
	v_mov_b64_e32 v[42:43], v[14:15]
	v_mov_b64_e32 v[44:45], v[12:13]
	v_mov_b64_e32 v[46:47], v[10:11]
	v_mov_b64_e32 v[48:49], v[8:9]
	v_mov_b64_e32 v[50:51], v[56:57]
	v_mov_b64_e32 v[52:53], v[54:55]
	s_branch .LBB0_169

; __device__ __forceinline__ unsigned xb_ld(unsigned* p)              { return __hip_atomic_load(p, __ATOMIC_RELAXED, __HIP_MEMORY_SCOPE_AGENT); }
; #define SEAM(k) do { if (args.coop == 2) cg::this_grid().sync(); else if (args.coop) xcd_barrier(gbar); } while (0)
; __device__ __forceinline__ void xcd_barrier_complete(unsigned* bar, unsigned x, unsigned& nloc, unsigned& nx) {
;     const unsigned G = gridDim.x * gridDim.y * gridDim.z;
;     unsigned sum, cnt, mine, sp = 0u;
;     for (;;) {
;         sum = 0u; cnt = 0u; mine = 0u;
; #pragma unroll
;         for (unsigned j = 0; j < 16; ++j) { const unsigned c = xb_ld(&bar[XB_XCNT(j)]); sum += c; cnt += (c > 0u) ? 1u : 0u; mine = (j == x) ? c : mine; }
; __device__ __forceinline__ void xcd_barrier(const XcdBarrier& b) {
;     asm volatile("s_waitcnt vmcnt(0)" ::: "memory");
;     __syncthreads();
;     if (threadIdx.x == 0) {
;         unsigned* bar = b.bar;
;         __builtin_amdgcn_s_waitcnt(0);
;         unsigned nloc = b.st[0], nx = b.st[1];
;         if (nloc == 0u) { xcd_barrier_complete(bar, b.x, nloc, nx); b.st[0] = nloc; b.st[1] = nx; }
; __global__ void __launch_bounds__(512, 2) mega_fwd(Args args) {
;     ...
;     SEAM(2);
.LBB0_336:
	s_setprio 0
	s_and_b64 vcc, exec, s[42:43]
	s_cbranch_vccz .LBB0_349
	s_mov_b64 s[4:5], 0
	s_cmp_lg_u32 s26, 0
	s_mov_b64 s[6:7], 0
	s_cbranch_scc0 .LBB0_350
	s_waitcnt vmcnt(0)
	s_waitcnt vmcnt(0)
	s_barrier
	s_and_saveexec_b64 s[6:7], s[86:87]
	s_cbranch_execz .LBB0_1341
	s_add_i32 s8, 0, 0x23ff0
	v_mov_b32_e32 v0, s8
	s_waitcnt vmcnt(0) expcnt(0) lgkmcnt(0)
	ds_read_b32 v2, v0
	s_add_i32 s8, 0, 0x23ff4
	v_mov_b32_e32 v0, s8
	ds_read_b32 v0, v0
	s_waitcnt lgkmcnt(1)
	v_cmp_ne_u32_e32 vcc, 0, v2
	s_cbranch_vccnz .LBB0_961
	s_load_dwordx2 s[18:19], s[82:83], 0x4
	s_add_u32 s8, s36, 0x2f000200
	s_addc_u32 s9, s37, 0
	s_add_u32 s10, s36, 0x2f000400
	s_addc_u32 s11, s37, 0
	s_waitcnt lgkmcnt(0)
	s_mul_i32 s13, s18, s3
	s_add_u32 s18, s36, 0x2f000500
	s_mul_i32 s13, s13, s19
	s_addc_u32 s19, s37, 0
	s_add_u32 s20, s36, 0x2f000600
	s_addc_u32 s21, s37, 0
	s_add_u32 s22, s36, 0x2f000700
	s_addc_u32 s23, s37, 0
	s_add_u32 s28, s36, 0x2f000800
	s_addc_u32 s29, s37, 0
	s_add_u32 s30, s36, 0x2f000900
	s_addc_u32 s31, s37, 0
	s_add_u32 s44, s36, 0x2f000a00
	s_addc_u32 s45, s37, 0
	s_add_u32 s46, s36, 0x2f000b00
	s_addc_u32 s47, s37, 0
	s_add_u32 s48, s36, 0x2f000c00
	s_addc_u32 s49, s37, 0
	s_add_u32 s50, s36, 0x2f000d00
	s_addc_u32 s51, s37, 0
	s_add_u32 s52, s36, 0x2f000e00
	s_addc_u32 s53, s37, 0
	s_add_u32 s54, s36, 0x2f000f00
	s_addc_u32 s55, s37, 0
	s_add_u32 s56, s36, 0x2f001000
	s_addc_u32 s57, s37, 0
	s_add_u32 s58, s36, 0x2f001100
	s_addc_u32 s59, s37, 0
	s_add_u32 s60, s36, 0x2f001200
	s_addc_u32 s61, s37, 0
	s_add_u32 s62, s36, 0x2f001300
	s_addc_u32 s63, s37, 0
	s_mov_b32 s15, 1
	v_mov_b32_e32 v16, 0
	s_branch .LBB0_342
